# GEMM bf16 epilogue: branch-free fast paths for mode 1/2 (one tile base address, row stepping by 64-bit add, global stores) + MIX_O block-id rotation
# baseline (speedup 1.0000x reference)
; __device__ __forceinline__ unsigned pk2(float lo, float hi) { f32x2c v = {lo, hi}; return __builtin_bit_cast(unsigned, __builtin_convertvector(v, bf16x2c)); }
; __device__ __forceinline__ float act_fn(float v, int mode) {
;     if (mode == 2) { v = fmaxf(v, 0.f); return v * v; }
;     if (mode == 3) { const float e = __expf(2.f * v); return 1.f - 2.f * __builtin_amdgcn_rcpf(e + 1.f); }
;     if (mode == 4) return __builtin_amdgcn_rcpf(1.f + __expf(-v));
; __device__ __forceinline__ void epilogue(const f32x4 (&acc)[2][2][4][2], const Unit& u, LAS unsigned char* lds, int wr, int wc, int fr, int fq) {
;     ...
;     } else {
;         bf16_t* C = (bf16_t*)Cp;
; #pragma unroll
;         for (int ai = 0; ai < 2; ++ai)
; #pragma unroll
;             for (int m = 0; m < 4; ++m) { bf16_t* rowp = C + (size_t)(row0 + ai * HALF + m * 16) * ldc + col0;
; #pragma unroll
;                 for (int bj = 0; bj < 2; ++bj)
; #pragma unroll
;                     for (int n = 0; n < 2; ++n) { const f32x4 v = acc[ai][bj][m][n]; u32x2 w;
;                         w.x = pk2(act_fn(v[0], mode), act_fn(v[1], mode)); w.y = pk2(act_fn(v[2], mode), act_fn(v[3], mode));
;                         *(u32x2*)(rowp + bj * HALF + n * 16) = w; } }
.LBB0_1311:
	s_cmp_eq_u32 s23, 1
	s_cbranch_scc1 .Lepi_m1
	s_cmp_eq_u32 s23, 2
	s_cbranch_scc1 .Lepi_m2
	s_cmp_lt_i32 s23, 3
	s_cbranch_scc1 .LBB0_1317
	s_cmp_gt_i32 s23, 3
	s_cbranch_scc0 .LBB0_1314
	v_mul_f32_e32 v141, 0xbfb8aa3b, v128
	v_exp_f32_e32 v141, v141
	s_mov_b64 s[2:3], 0
	v_add_f32_e32 v141, 1.0, v141
	v_rcp_f32_e32 v141, v141

; __device__ __forceinline__ unsigned pk2(float lo, float hi) { f32x2c v = {lo, hi}; return __builtin_bit_cast(unsigned, __builtin_convertvector(v, bf16x2c)); }
; __device__ __forceinline__ void epilogue(const f32x4 (&acc)[2][2][4][2], const Unit& u, LAS unsigned char* lds, int wr, int wc, int fr, int fq) {
;     ...
;         bf16_t* C = (bf16_t*)Cp;
; #pragma unroll
;         for (int ai = 0; ai < 2; ++ai)
; #pragma unroll
;             for (int m = 0; m < 4; ++m) { bf16_t* rowp = C + (size_t)(row0 + ai * HALF + m * 16) * ldc + col0;
; #pragma unroll
;                 for (int bj = 0; bj < 2; ++bj)
; #pragma unroll
;                     for (int n = 0; n < 2; ++n) { const f32x4 v = acc[ai][bj][m][n]; u32x2 w;
;                         w.x = pk2(act_fn(v[0], mode), act_fn(v[1], mode)); w.y = pk2(act_fn(v[2], mode), act_fn(v[3], mode));
;                         *(u32x2*)(rowp + bj * HALF + n * 16) = w; } }
.Lepi_m1:
	v_ashrrev_i32_e32 v141, 31, v140
	v_lshl_add_u64 v[142:143], v[140:141], 1, s[8:9]
	v_ashrrev_i32_e32 v141, 31, v161
	v_mul_lo_u32 v165, s27, v161
	v_mul_lo_u32 v141, s26, v141
	v_mad_u64_u32 v[144:145], vcc, s26, v161, 0
	v_add3_u32 v145, v145, v141, v165
	v_lshl_add_u64 v[144:145], v[144:145], 1, v[142:143]
	s_lshl_b64 s[2:3], s[26:27], 5
	v_cvt_pk_bf16_f32 v162, v128, v129
	v_cvt_pk_bf16_f32 v163, v130, v131
	global_store_dwordx2 v[144:145], v[162:163], off
	v_cvt_pk_bf16_f32 v164, v124, v125
	v_cvt_pk_bf16_f32 v165, v126, v127
	global_store_dwordx2 v[144:145], v[164:165], off offset:32
	v_cvt_pk_bf16_f32 v236, v120, v121
	v_cvt_pk_bf16_f32 v237, v122, v123
	global_store_dwordx2 v[144:145], v[236:237], off offset:256
	v_cvt_pk_bf16_f32 v238, v116, v117
	v_cvt_pk_bf16_f32 v239, v118, v119
	global_store_dwordx2 v[144:145], v[238:239], off offset:288
	v_lshl_add_u64 v[144:145], s[2:3], 0, v[144:145]
	v_cvt_pk_bf16_f32 v162, v112, v113
	v_cvt_pk_bf16_f32 v163, v114, v115
	global_store_dwordx2 v[144:145], v[162:163], off
	v_cvt_pk_bf16_f32 v164, v108, v109
	v_cvt_pk_bf16_f32 v165, v110, v111
	global_store_dwordx2 v[144:145], v[164:165], off offset:32
	v_cvt_pk_bf16_f32 v236, v104, v105
	v_cvt_pk_bf16_f32 v237, v106, v107
	global_store_dwordx2 v[144:145], v[236:237], off offset:256
	v_cvt_pk_bf16_f32 v238, v100, v101
	v_cvt_pk_bf16_f32 v239, v102, v103
	global_store_dwordx2 v[144:145], v[238:239], off offset:288
	v_lshl_add_u64 v[144:145], s[2:3], 0, v[144:145]
	v_cvt_pk_bf16_f32 v162, v96, v97
	v_cvt_pk_bf16_f32 v163, v98, v99
	global_store_dwordx2 v[144:145], v[162:163], off
	v_cvt_pk_bf16_f32 v164, v92, v93
	v_cvt_pk_bf16_f32 v165, v94, v95
	global_store_dwordx2 v[144:145], v[164:165], off offset:32
	v_cvt_pk_bf16_f32 v236, v88, v89
	v_cvt_pk_bf16_f32 v237, v90, v91
	global_store_dwordx2 v[144:145], v[236:237], off offset:256
	v_cvt_pk_bf16_f32 v238, v84, v85
	v_cvt_pk_bf16_f32 v239, v86, v87
	global_store_dwordx2 v[144:145], v[238:239], off offset:288
	v_lshl_add_u64 v[144:145], s[2:3], 0, v[144:145]
	v_cvt_pk_bf16_f32 v162, v80, v81
	v_cvt_pk_bf16_f32 v163, v82, v83
	global_store_dwordx2 v[144:145], v[162:163], off
	v_cvt_pk_bf16_f32 v164, v76, v77
	v_cvt_pk_bf16_f32 v165, v78, v79
	global_store_dwordx2 v[144:145], v[164:165], off offset:32
	v_cvt_pk_bf16_f32 v236, v72, v73
	v_cvt_pk_bf16_f32 v237, v74, v75
	global_store_dwordx2 v[144:145], v[236:237], off offset:256
	v_cvt_pk_bf16_f32 v238, v68, v69
	v_cvt_pk_bf16_f32 v239, v70, v71
	global_store_dwordx2 v[144:145], v[238:239], off offset:288
	v_lshl_add_u64 v[144:145], s[2:3], 2, v[144:145]
	v_lshl_add_u64 v[144:145], s[2:3], 0, v[144:145]
	v_cvt_pk_bf16_f32 v162, v64, v65
	v_cvt_pk_bf16_f32 v163, v66, v67
	global_store_dwordx2 v[144:145], v[162:163], off
	v_cvt_pk_bf16_f32 v164, v60, v61
	v_cvt_pk_bf16_f32 v165, v62, v63
	global_store_dwordx2 v[144:145], v[164:165], off offset:32
	v_cvt_pk_bf16_f32 v236, v56, v57
	v_cvt_pk_bf16_f32 v237, v58, v59
	global_store_dwordx2 v[144:145], v[236:237], off offset:256
	v_cvt_pk_bf16_f32 v238, v52, v53
	v_cvt_pk_bf16_f32 v239, v54, v55
	global_store_dwordx2 v[144:145], v[238:239], off offset:288
	v_lshl_add_u64 v[144:145], s[2:3], 0, v[144:145]
	v_cvt_pk_bf16_f32 v162, v48, v49
	v_cvt_pk_bf16_f32 v163, v50, v51
	global_store_dwordx2 v[144:145], v[162:163], off
	v_cvt_pk_bf16_f32 v164, v44, v45
	v_cvt_pk_bf16_f32 v165, v46, v47
	global_store_dwordx2 v[144:145], v[164:165], off offset:32
	v_cvt_pk_bf16_f32 v236, v40, v41
	v_cvt_pk_bf16_f32 v237, v42, v43
	global_store_dwordx2 v[144:145], v[236:237], off offset:256
	v_cvt_pk_bf16_f32 v238, v36, v37
	v_cvt_pk_bf16_f32 v239, v38, v39
	global_store_dwordx2 v[144:145], v[238:239], off offset:288
	v_lshl_add_u64 v[144:145], s[2:3], 0, v[144:145]
	v_cvt_pk_bf16_f32 v162, v32, v33
	v_cvt_pk_bf16_f32 v163, v34, v35
	global_store_dwordx2 v[144:145], v[162:163], off
	v_cvt_pk_bf16_f32 v164, v28, v29
	v_cvt_pk_bf16_f32 v165, v30, v31
	global_store_dwordx2 v[144:145], v[164:165], off offset:32
	v_cvt_pk_bf16_f32 v236, v24, v25
	v_cvt_pk_bf16_f32 v237, v26, v27
	global_store_dwordx2 v[144:145], v[236:237], off offset:256
	v_cvt_pk_bf16_f32 v238, v20, v21
	v_cvt_pk_bf16_f32 v239, v22, v23
	global_store_dwordx2 v[144:145], v[238:239], off offset:288
	v_lshl_add_u64 v[144:145], s[2:3], 0, v[144:145]
	v_cvt_pk_bf16_f32 v162, v16, v17
	v_cvt_pk_bf16_f32 v163, v18, v19
	global_store_dwordx2 v[144:145], v[162:163], off
	v_cvt_pk_bf16_f32 v164, v12, v13
	v_cvt_pk_bf16_f32 v165, v14, v15
	global_store_dwordx2 v[144:145], v[164:165], off offset:32
	v_cvt_pk_bf16_f32 v236, v8, v9
	v_cvt_pk_bf16_f32 v237, v10, v11
	global_store_dwordx2 v[144:145], v[236:237], off offset:256
	v_cvt_pk_bf16_f32 v238, v4, v5
	v_cvt_pk_bf16_f32 v239, v6, v7
	global_store_dwordx2 v[144:145], v[238:239], off offset:288
	s_branch .LBB0_1310
; __device__ __forceinline__ unsigned pk2(float lo, float hi) { f32x2c v = {lo, hi}; return __builtin_bit_cast(unsigned, __builtin_convertvector(v, bf16x2c)); }
; __device__ __forceinline__ float act_fn(float v, int mode) {
;     if (mode == 2) { v = fmaxf(v, 0.f); return v * v; }
; __device__ __forceinline__ void epilogue(const f32x4 (&acc)[2][2][4][2], const Unit& u, LAS unsigned char* lds, int wr, int wc, int fr, int fq) {
;     ...
;             for (int m = 0; m < 4; ++m) { bf16_t* rowp = C + (size_t)(row0 + ai * HALF + m * 16) * ldc + col0;
; #pragma unroll
;                 for (int bj = 0; bj < 2; ++bj)
; #pragma unroll
;                     for (int n = 0; n < 2; ++n) { const f32x4 v = acc[ai][bj][m][n]; u32x2 w;
;                         w.x = pk2(act_fn(v[0], mode), act_fn(v[1], mode)); w.y = pk2(act_fn(v[2], mode), act_fn(v[3], mode));
;                         *(u32x2*)(rowp + bj * HALF + n * 16) = w; } }
.Lepi_m2:
	v_ashrrev_i32_e32 v141, 31, v140
	v_lshl_add_u64 v[142:143], v[140:141], 1, s[8:9]
	v_ashrrev_i32_e32 v141, 31, v161
	v_mul_lo_u32 v165, s27, v161
	v_mul_lo_u32 v141, s26, v141
	v_mad_u64_u32 v[144:145], vcc, s26, v161, 0
	v_add3_u32 v145, v145, v141, v165
	v_lshl_add_u64 v[144:145], v[144:145], 1, v[142:143]
	s_lshl_b64 s[2:3], s[26:27], 5
	v_max_f32_e32 v240, v128, v128
	v_max_f32_e32 v241, v129, v129
	v_max_f32_e32 v242, v130, v130
	v_max_f32_e32 v243, v131, v131
	v_max_f32_e32 v240, 0, v240
	v_max_f32_e32 v241, 0, v241
	v_max_f32_e32 v242, 0, v242
	v_max_f32_e32 v243, 0, v243
	v_mul_f32_e32 v240, v240, v240
	v_mul_f32_e32 v241, v241, v241
	v_mul_f32_e32 v242, v242, v242
	v_mul_f32_e32 v243, v243, v243
	v_cvt_pk_bf16_f32 v162, v240, v241
	v_cvt_pk_bf16_f32 v163, v242, v243
	global_store_dwordx2 v[144:145], v[162:163], off
	v_max_f32_e32 v240, v124, v124
	v_max_f32_e32 v241, v125, v125
	v_max_f32_e32 v242, v126, v126
	v_max_f32_e32 v243, v127, v127
	v_max_f32_e32 v240, 0, v240
	v_max_f32_e32 v241, 0, v241
	v_max_f32_e32 v242, 0, v242
	v_max_f32_e32 v243, 0, v243
	v_mul_f32_e32 v240, v240, v240
	v_mul_f32_e32 v241, v241, v241
	v_mul_f32_e32 v242, v242, v242
	v_mul_f32_e32 v243, v243, v243
	v_cvt_pk_bf16_f32 v164, v240, v241
	v_cvt_pk_bf16_f32 v165, v242, v243
	global_store_dwordx2 v[144:145], v[164:165], off offset:32
	v_max_f32_e32 v240, v120, v120
	v_max_f32_e32 v241, v121, v121
	v_max_f32_e32 v242, v122, v122
	v_max_f32_e32 v243, v123, v123
	v_max_f32_e32 v240, 0, v240
	v_max_f32_e32 v241, 0, v241
	v_max_f32_e32 v242, 0, v242
	v_max_f32_e32 v243, 0, v243
	v_mul_f32_e32 v240, v240, v240
	v_mul_f32_e32 v241, v241, v241
	v_mul_f32_e32 v242, v242, v242
	v_mul_f32_e32 v243, v243, v243
	v_cvt_pk_bf16_f32 v236, v240, v241
	v_cvt_pk_bf16_f32 v237, v242, v243
	global_store_dwordx2 v[144:145], v[236:237], off offset:256
	v_max_f32_e32 v240, v116, v116
	v_max_f32_e32 v241, v117, v117
	v_max_f32_e32 v242, v118, v118
	v_max_f32_e32 v243, v119, v119
	v_max_f32_e32 v240, 0, v240
	v_max_f32_e32 v241, 0, v241
	v_max_f32_e32 v242, 0, v242
	v_max_f32_e32 v243, 0, v243
	v_mul_f32_e32 v240, v240, v240
	v_mul_f32_e32 v241, v241, v241
	v_mul_f32_e32 v242, v242, v242
	v_mul_f32_e32 v243, v243, v243
	v_cvt_pk_bf16_f32 v238, v240, v241
	v_cvt_pk_bf16_f32 v239, v242, v243
	global_store_dwordx2 v[144:145], v[238:239], off offset:288
	v_lshl_add_u64 v[144:145], s[2:3], 0, v[144:145]
	v_max_f32_e32 v240, v112, v112
	v_max_f32_e32 v241, v113, v113
	v_max_f32_e32 v242, v114, v114
	v_max_f32_e32 v243, v115, v115
	v_max_f32_e32 v240, 0, v240
	v_max_f32_e32 v241, 0, v241
	v_max_f32_e32 v242, 0, v242
	v_max_f32_e32 v243, 0, v243
	v_mul_f32_e32 v240, v240, v240
	v_mul_f32_e32 v241, v241, v241
	v_mul_f32_e32 v242, v242, v242
	v_mul_f32_e32 v243, v243, v243
	v_cvt_pk_bf16_f32 v162, v240, v241
	v_cvt_pk_bf16_f32 v163, v242, v243
	global_store_dwordx2 v[144:145], v[162:163], off
	v_max_f32_e32 v240, v108, v108
	v_max_f32_e32 v241, v109, v109
	v_max_f32_e32 v242, v110, v110
	v_max_f32_e32 v243, v111, v111
	v_max_f32_e32 v240, 0, v240
	v_max_f32_e32 v241, 0, v241
	v_max_f32_e32 v242, 0, v242
	v_max_f32_e32 v243, 0, v243
	v_mul_f32_e32 v240, v240, v240
	v_mul_f32_e32 v241, v241, v241
	v_mul_f32_e32 v242, v242, v242
	v_mul_f32_e32 v243, v243, v243
	v_cvt_pk_bf16_f32 v164, v240, v241
	v_cvt_pk_bf16_f32 v165, v242, v243
	global_store_dwordx2 v[144:145], v[164:165], off offset:32
	v_max_f32_e32 v240, v104, v104
	v_max_f32_e32 v241, v105, v105
	v_max_f32_e32 v242, v106, v106
	v_max_f32_e32 v243, v107, v107
	v_max_f32_e32 v240, 0, v240
	v_max_f32_e32 v241, 0, v241
	v_max_f32_e32 v242, 0, v242
	v_max_f32_e32 v243, 0, v243
	v_mul_f32_e32 v240, v240, v240
	v_mul_f32_e32 v241, v241, v241
	v_mul_f32_e32 v242, v242, v242
	v_mul_f32_e32 v243, v243, v243
	v_cvt_pk_bf16_f32 v236, v240, v241
	v_cvt_pk_bf16_f32 v237, v242, v243
	global_store_dwordx2 v[144:145], v[236:237], off offset:256
	v_max_f32_e32 v240, v100, v100
	v_max_f32_e32 v241, v101, v101
	v_max_f32_e32 v242, v102, v102
	v_max_f32_e32 v243, v103, v103
	v_max_f32_e32 v240, 0, v240
	v_max_f32_e32 v241, 0, v241
	v_max_f32_e32 v242, 0, v242
	v_max_f32_e32 v243, 0, v243
	v_mul_f32_e32 v240, v240, v240
	v_mul_f32_e32 v241, v241, v241
	v_mul_f32_e32 v242, v242, v242
	v_mul_f32_e32 v243, v243, v243
	v_cvt_pk_bf16_f32 v238, v240, v241
	v_cvt_pk_bf16_f32 v239, v242, v243
	global_store_dwordx2 v[144:145], v[238:239], off offset:288
	v_lshl_add_u64 v[144:145], s[2:3], 0, v[144:145]
	v_max_f32_e32 v240, v96, v96
	v_max_f32_e32 v241, v97, v97
	v_max_f32_e32 v242, v98, v98
	v_max_f32_e32 v243, v99, v99
	v_max_f32_e32 v240, 0, v240
	v_max_f32_e32 v241, 0, v241
	v_max_f32_e32 v242, 0, v242
	v_max_f32_e32 v243, 0, v243
	v_mul_f32_e32 v240, v240, v240
	v_mul_f32_e32 v241, v241, v241
	v_mul_f32_e32 v242, v242, v242
	v_mul_f32_e32 v243, v243, v243
	v_cvt_pk_bf16_f32 v162, v240, v241
	v_cvt_pk_bf16_f32 v163, v242, v243
	global_store_dwordx2 v[144:145], v[162:163], off
	v_max_f32_e32 v240, v92, v92
	v_max_f32_e32 v241, v93, v93
	v_max_f32_e32 v242, v94, v94
	v_max_f32_e32 v243, v95, v95
	v_max_f32_e32 v240, 0, v240
	v_max_f32_e32 v241, 0, v241
	v_max_f32_e32 v242, 0, v242
	v_max_f32_e32 v243, 0, v243
	v_mul_f32_e32 v240, v240, v240
	v_mul_f32_e32 v241, v241, v241
	v_mul_f32_e32 v242, v242, v242
	v_mul_f32_e32 v243, v243, v243
	v_cvt_pk_bf16_f32 v164, v240, v241
	v_cvt_pk_bf16_f32 v165, v242, v243
	global_store_dwordx2 v[144:145], v[164:165], off offset:32
	v_max_f32_e32 v240, v88, v88
	v_max_f32_e32 v241, v89, v89
	v_max_f32_e32 v242, v90, v90
	v_max_f32_e32 v243, v91, v91
	v_max_f32_e32 v240, 0, v240
	v_max_f32_e32 v241, 0, v241
; __device__ __forceinline__ unsigned pk2(float lo, float hi) { f32x2c v = {lo, hi}; return __builtin_bit_cast(unsigned, __builtin_convertvector(v, bf16x2c)); }
; __device__ __forceinline__ float act_fn(float v, int mode) {
;     if (mode == 2) { v = fmaxf(v, 0.f); return v * v; }
; __device__ __forceinline__ void epilogue(const f32x4 (&acc)[2][2][4][2], const Unit& u, LAS unsigned char* lds, int wr, int wc, int fr, int fq) {
;     ...
;             for (int m = 0; m < 4; ++m) { bf16_t* rowp = C + (size_t)(row0 + ai * HALF + m * 16) * ldc + col0;
; #pragma unroll
;                 for (int bj = 0; bj < 2; ++bj)
; #pragma unroll
;                     for (int n = 0; n < 2; ++n) { const f32x4 v = acc[ai][bj][m][n]; u32x2 w;
;                         w.x = pk2(act_fn(v[0], mode), act_fn(v[1], mode)); w.y = pk2(act_fn(v[2], mode), act_fn(v[3], mode));
;                         *(u32x2*)(rowp + bj * HALF + n * 16) = w; } }
	v_max_f32_e32 v242, 0, v242
	v_max_f32_e32 v243, 0, v243
	v_mul_f32_e32 v240, v240, v240
	v_mul_f32_e32 v241, v241, v241
	v_mul_f32_e32 v242, v242, v242
	v_mul_f32_e32 v243, v243, v243
	v_cvt_pk_bf16_f32 v236, v240, v241
	v_cvt_pk_bf16_f32 v237, v242, v243
	global_store_dwordx2 v[144:145], v[236:237], off offset:256
	v_max_f32_e32 v240, v84, v84
	v_max_f32_e32 v241, v85, v85
	v_max_f32_e32 v242, v86, v86
	v_max_f32_e32 v243, v87, v87
	v_max_f32_e32 v240, 0, v240
	v_max_f32_e32 v241, 0, v241
	v_max_f32_e32 v242, 0, v242
	v_max_f32_e32 v243, 0, v243
	v_mul_f32_e32 v240, v240, v240
	v_mul_f32_e32 v241, v241, v241
	v_mul_f32_e32 v242, v242, v242
	v_mul_f32_e32 v243, v243, v243
	v_cvt_pk_bf16_f32 v238, v240, v241
	v_cvt_pk_bf16_f32 v239, v242, v243
	global_store_dwordx2 v[144:145], v[238:239], off offset:288
	v_lshl_add_u64 v[144:145], s[2:3], 0, v[144:145]
	v_max_f32_e32 v240, v80, v80
	v_max_f32_e32 v241, v81, v81
	v_max_f32_e32 v242, v82, v82
	v_max_f32_e32 v243, v83, v83
	v_max_f32_e32 v240, 0, v240
	v_max_f32_e32 v241, 0, v241
	v_max_f32_e32 v242, 0, v242
	v_max_f32_e32 v243, 0, v243
	v_mul_f32_e32 v240, v240, v240
	v_mul_f32_e32 v241, v241, v241
	v_mul_f32_e32 v242, v242, v242
	v_mul_f32_e32 v243, v243, v243
	v_cvt_pk_bf16_f32 v162, v240, v241
	v_cvt_pk_bf16_f32 v163, v242, v243
	global_store_dwordx2 v[144:145], v[162:163], off
	v_max_f32_e32 v240, v76, v76
	v_max_f32_e32 v241, v77, v77
	v_max_f32_e32 v242, v78, v78
	v_max_f32_e32 v243, v79, v79
	v_max_f32_e32 v240, 0, v240
	v_max_f32_e32 v241, 0, v241
	v_max_f32_e32 v242, 0, v242
	v_max_f32_e32 v243, 0, v243
	v_mul_f32_e32 v240, v240, v240
	v_mul_f32_e32 v241, v241, v241
	v_mul_f32_e32 v242, v242, v242
	v_mul_f32_e32 v243, v243, v243
	v_cvt_pk_bf16_f32 v164, v240, v241
	v_cvt_pk_bf16_f32 v165, v242, v243
	global_store_dwordx2 v[144:145], v[164:165], off offset:32
	v_max_f32_e32 v240, v72, v72
	v_max_f32_e32 v241, v73, v73
	v_max_f32_e32 v242, v74, v74
	v_max_f32_e32 v243, v75, v75
	v_max_f32_e32 v240, 0, v240
	v_max_f32_e32 v241, 0, v241
	v_max_f32_e32 v242, 0, v242
	v_max_f32_e32 v243, 0, v243
	v_mul_f32_e32 v240, v240, v240
	v_mul_f32_e32 v241, v241, v241
	v_mul_f32_e32 v242, v242, v242
	v_mul_f32_e32 v243, v243, v243
	v_cvt_pk_bf16_f32 v236, v240, v241
	v_cvt_pk_bf16_f32 v237, v242, v243
	global_store_dwordx2 v[144:145], v[236:237], off offset:256
	v_max_f32_e32 v240, v68, v68
	v_max_f32_e32 v241, v69, v69
	v_max_f32_e32 v242, v70, v70
	v_max_f32_e32 v243, v71, v71
	v_max_f32_e32 v240, 0, v240
	v_max_f32_e32 v241, 0, v241
	v_max_f32_e32 v242, 0, v242
	v_max_f32_e32 v243, 0, v243
	v_mul_f32_e32 v240, v240, v240
	v_mul_f32_e32 v241, v241, v241
	v_mul_f32_e32 v242, v242, v242
	v_mul_f32_e32 v243, v243, v243
	v_cvt_pk_bf16_f32 v238, v240, v241
	v_cvt_pk_bf16_f32 v239, v242, v243
	global_store_dwordx2 v[144:145], v[238:239], off offset:288
	v_lshl_add_u64 v[144:145], s[2:3], 2, v[144:145]
	v_lshl_add_u64 v[144:145], s[2:3], 0, v[144:145]
	v_max_f32_e32 v240, v64, v64
	v_max_f32_e32 v241, v65, v65
	v_max_f32_e32 v242, v66, v66
	v_max_f32_e32 v243, v67, v67
	v_max_f32_e32 v240, 0, v240
	v_max_f32_e32 v241, 0, v241
	v_max_f32_e32 v242, 0, v242
	v_max_f32_e32 v243, 0, v243
	v_mul_f32_e32 v240, v240, v240
	v_mul_f32_e32 v241, v241, v241
	v_mul_f32_e32 v242, v242, v242
	v_mul_f32_e32 v243, v243, v243
	v_cvt_pk_bf16_f32 v162, v240, v241
	v_cvt_pk_bf16_f32 v163, v242, v243
	global_store_dwordx2 v[144:145], v[162:163], off
	v_max_f32_e32 v240, v60, v60
	v_max_f32_e32 v241, v61, v61
	v_max_f32_e32 v242, v62, v62
	v_max_f32_e32 v243, v63, v63
	v_max_f32_e32 v240, 0, v240
	v_max_f32_e32 v241, 0, v241
	v_max_f32_e32 v242, 0, v242
	v_max_f32_e32 v243, 0, v243
	v_mul_f32_e32 v240, v240, v240
	v_mul_f32_e32 v241, v241, v241
	v_mul_f32_e32 v242, v242, v242
	v_mul_f32_e32 v243, v243, v243
	v_cvt_pk_bf16_f32 v164, v240, v241
	v_cvt_pk_bf16_f32 v165, v242, v243
	global_store_dwordx2 v[144:145], v[164:165], off offset:32
	v_max_f32_e32 v240, v56, v56
	v_max_f32_e32 v241, v57, v57
	v_max_f32_e32 v242, v58, v58
	v_max_f32_e32 v243, v59, v59
	v_max_f32_e32 v240, 0, v240
	v_max_f32_e32 v241, 0, v241
	v_max_f32_e32 v242, 0, v242
	v_max_f32_e32 v243, 0, v243
	v_mul_f32_e32 v240, v240, v240
	v_mul_f32_e32 v241, v241, v241
	v_mul_f32_e32 v242, v242, v242
	v_mul_f32_e32 v243, v243, v243
	v_cvt_pk_bf16_f32 v236, v240, v241
	v_cvt_pk_bf16_f32 v237, v242, v243
	global_store_dwordx2 v[144:145], v[236:237], off offset:256
	v_max_f32_e32 v240, v52, v52
	v_max_f32_e32 v241, v53, v53
	v_max_f32_e32 v242, v54, v54
	v_max_f32_e32 v243, v55, v55
	v_max_f32_e32 v240, 0, v240
	v_max_f32_e32 v241, 0, v241
	v_max_f32_e32 v242, 0, v242
	v_max_f32_e32 v243, 0, v243
	v_mul_f32_e32 v240, v240, v240
	v_mul_f32_e32 v241, v241, v241
	v_mul_f32_e32 v242, v242, v242
	v_mul_f32_e32 v243, v243, v243
	v_cvt_pk_bf16_f32 v238, v240, v241
	v_cvt_pk_bf16_f32 v239, v242, v243
	global_store_dwordx2 v[144:145], v[238:239], off offset:288
	v_lshl_add_u64 v[144:145], s[2:3], 0, v[144:145]
	v_max_f32_e32 v240, v48, v48
	v_max_f32_e32 v241, v49, v49
	v_max_f32_e32 v242, v50, v50
	v_max_f32_e32 v243, v51, v51
	v_max_f32_e32 v240, 0, v240
	v_max_f32_e32 v241, 0, v241
	v_max_f32_e32 v242, 0, v242
	v_max_f32_e32 v243, 0, v243
	v_mul_f32_e32 v240, v240, v240
	v_mul_f32_e32 v241, v241, v241
	v_mul_f32_e32 v242, v242, v242
	v_mul_f32_e32 v243, v243, v243
	v_cvt_pk_bf16_f32 v162, v240, v241
	v_cvt_pk_bf16_f32 v163, v242, v243
	global_store_dwordx2 v[144:145], v[162:163], off
	v_max_f32_e32 v240, v44, v44
	v_max_f32_e32 v241, v45, v45
; __device__ __forceinline__ unsigned pk2(float lo, float hi) { f32x2c v = {lo, hi}; return __builtin_bit_cast(unsigned, __builtin_convertvector(v, bf16x2c)); }
; __device__ __forceinline__ float act_fn(float v, int mode) {
;     if (mode == 2) { v = fmaxf(v, 0.f); return v * v; }
; __device__ __forceinline__ void epilogue(const f32x4 (&acc)[2][2][4][2], const Unit& u, LAS unsigned char* lds, int wr, int wc, int fr, int fq) {
;     ...
;             for (int m = 0; m < 4; ++m) { bf16_t* rowp = C + (size_t)(row0 + ai * HALF + m * 16) * ldc + col0;
; #pragma unroll
;                 for (int bj = 0; bj < 2; ++bj)
; #pragma unroll
;                     for (int n = 0; n < 2; ++n) { const f32x4 v = acc[ai][bj][m][n]; u32x2 w;
;                         w.x = pk2(act_fn(v[0], mode), act_fn(v[1], mode)); w.y = pk2(act_fn(v[2], mode), act_fn(v[3], mode));
;                         *(u32x2*)(rowp + bj * HALF + n * 16) = w; } }
	v_max_f32_e32 v242, v46, v46
	v_max_f32_e32 v243, v47, v47
	v_max_f32_e32 v240, 0, v240
	v_max_f32_e32 v241, 0, v241
	v_max_f32_e32 v242, 0, v242
	v_max_f32_e32 v243, 0, v243
	v_mul_f32_e32 v240, v240, v240
	v_mul_f32_e32 v241, v241, v241
	v_mul_f32_e32 v242, v242, v242
	v_mul_f32_e32 v243, v243, v243
	v_cvt_pk_bf16_f32 v164, v240, v241
	v_cvt_pk_bf16_f32 v165, v242, v243
	global_store_dwordx2 v[144:145], v[164:165], off offset:32
	v_max_f32_e32 v240, v40, v40
	v_max_f32_e32 v241, v41, v41
	v_max_f32_e32 v242, v42, v42
	v_max_f32_e32 v243, v43, v43
	v_max_f32_e32 v240, 0, v240
	v_max_f32_e32 v241, 0, v241
	v_max_f32_e32 v242, 0, v242
	v_max_f32_e32 v243, 0, v243
	v_mul_f32_e32 v240, v240, v240
	v_mul_f32_e32 v241, v241, v241
	v_mul_f32_e32 v242, v242, v242
	v_mul_f32_e32 v243, v243, v243
	v_cvt_pk_bf16_f32 v236, v240, v241
	v_cvt_pk_bf16_f32 v237, v242, v243
	global_store_dwordx2 v[144:145], v[236:237], off offset:256
	v_max_f32_e32 v240, v36, v36
	v_max_f32_e32 v241, v37, v37
	v_max_f32_e32 v242, v38, v38
	v_max_f32_e32 v243, v39, v39
	v_max_f32_e32 v240, 0, v240
	v_max_f32_e32 v241, 0, v241
	v_max_f32_e32 v242, 0, v242
	v_max_f32_e32 v243, 0, v243
	v_mul_f32_e32 v240, v240, v240
	v_mul_f32_e32 v241, v241, v241
	v_mul_f32_e32 v242, v242, v242
	v_mul_f32_e32 v243, v243, v243
	v_cvt_pk_bf16_f32 v238, v240, v241
	v_cvt_pk_bf16_f32 v239, v242, v243
	global_store_dwordx2 v[144:145], v[238:239], off offset:288
	v_lshl_add_u64 v[144:145], s[2:3], 0, v[144:145]
	v_max_f32_e32 v240, v32, v32
	v_max_f32_e32 v241, v33, v33
	v_max_f32_e32 v242, v34, v34
	v_max_f32_e32 v243, v35, v35
	v_max_f32_e32 v240, 0, v240
	v_max_f32_e32 v241, 0, v241
	v_max_f32_e32 v242, 0, v242
	v_max_f32_e32 v243, 0, v243
	v_mul_f32_e32 v240, v240, v240
	v_mul_f32_e32 v241, v241, v241
	v_mul_f32_e32 v242, v242, v242
	v_mul_f32_e32 v243, v243, v243
	v_cvt_pk_bf16_f32 v162, v240, v241
	v_cvt_pk_bf16_f32 v163, v242, v243
	global_store_dwordx2 v[144:145], v[162:163], off
	v_max_f32_e32 v240, v28, v28
	v_max_f32_e32 v241, v29, v29
	v_max_f32_e32 v242, v30, v30
	v_max_f32_e32 v243, v31, v31
	v_max_f32_e32 v240, 0, v240
	v_max_f32_e32 v241, 0, v241
	v_max_f32_e32 v242, 0, v242
	v_max_f32_e32 v243, 0, v243
	v_mul_f32_e32 v240, v240, v240
	v_mul_f32_e32 v241, v241, v241
	v_mul_f32_e32 v242, v242, v242
	v_mul_f32_e32 v243, v243, v243
	v_cvt_pk_bf16_f32 v164, v240, v241
	v_cvt_pk_bf16_f32 v165, v242, v243
	global_store_dwordx2 v[144:145], v[164:165], off offset:32
	v_max_f32_e32 v240, v24, v24
	v_max_f32_e32 v241, v25, v25
	v_max_f32_e32 v242, v26, v26
	v_max_f32_e32 v243, v27, v27
	v_max_f32_e32 v240, 0, v240
	v_max_f32_e32 v241, 0, v241
	v_max_f32_e32 v242, 0, v242
	v_max_f32_e32 v243, 0, v243
	v_mul_f32_e32 v240, v240, v240
	v_mul_f32_e32 v241, v241, v241
	v_mul_f32_e32 v242, v242, v242
	v_mul_f32_e32 v243, v243, v243
	v_cvt_pk_bf16_f32 v236, v240, v241
	v_cvt_pk_bf16_f32 v237, v242, v243
	global_store_dwordx2 v[144:145], v[236:237], off offset:256
	v_max_f32_e32 v240, v20, v20
	v_max_f32_e32 v241, v21, v21
	v_max_f32_e32 v242, v22, v22
	v_max_f32_e32 v243, v23, v23
	v_max_f32_e32 v240, 0, v240
	v_max_f32_e32 v241, 0, v241
	v_max_f32_e32 v242, 0, v242
	v_max_f32_e32 v243, 0, v243
	v_mul_f32_e32 v240, v240, v240
	v_mul_f32_e32 v241, v241, v241
	v_mul_f32_e32 v242, v242, v242
	v_mul_f32_e32 v243, v243, v243
	v_cvt_pk_bf16_f32 v238, v240, v241
	v_cvt_pk_bf16_f32 v239, v242, v243
	global_store_dwordx2 v[144:145], v[238:239], off offset:288
	v_lshl_add_u64 v[144:145], s[2:3], 0, v[144:145]
	v_max_f32_e32 v240, v16, v16
	v_max_f32_e32 v241, v17, v17
	v_max_f32_e32 v242, v18, v18
	v_max_f32_e32 v243, v19, v19
	v_max_f32_e32 v240, 0, v240
	v_max_f32_e32 v241, 0, v241
	v_max_f32_e32 v242, 0, v242
	v_max_f32_e32 v243, 0, v243
	v_mul_f32_e32 v240, v240, v240
	v_mul_f32_e32 v241, v241, v241
	v_mul_f32_e32 v242, v242, v242
	v_mul_f32_e32 v243, v243, v243
	v_cvt_pk_bf16_f32 v162, v240, v241
	v_cvt_pk_bf16_f32 v163, v242, v243
	global_store_dwordx2 v[144:145], v[162:163], off
	v_max_f32_e32 v240, v12, v12
	v_max_f32_e32 v241, v13, v13
	v_max_f32_e32 v242, v14, v14
	v_max_f32_e32 v243, v15, v15
	v_max_f32_e32 v240, 0, v240
	v_max_f32_e32 v241, 0, v241
	v_max_f32_e32 v242, 0, v242
	v_max_f32_e32 v243, 0, v243
	v_mul_f32_e32 v240, v240, v240
	v_mul_f32_e32 v241, v241, v241
	v_mul_f32_e32 v242, v242, v242
	v_mul_f32_e32 v243, v243, v243
	v_cvt_pk_bf16_f32 v164, v240, v241
	v_cvt_pk_bf16_f32 v165, v242, v243
	global_store_dwordx2 v[144:145], v[164:165], off offset:32
	v_max_f32_e32 v240, v8, v8
	v_max_f32_e32 v241, v9, v9
	v_max_f32_e32 v242, v10, v10
	v_max_f32_e32 v243, v11, v11
	v_max_f32_e32 v240, 0, v240
	v_max_f32_e32 v241, 0, v241
	v_max_f32_e32 v242, 0, v242
	v_max_f32_e32 v243, 0, v243
	v_mul_f32_e32 v240, v240, v240
	v_mul_f32_e32 v241, v241, v241
	v_mul_f32_e32 v242, v242, v242
	v_mul_f32_e32 v243, v243, v243
	v_cvt_pk_bf16_f32 v236, v240, v241
	v_cvt_pk_bf16_f32 v237, v242, v243
	global_store_dwordx2 v[144:145], v[236:237], off offset:256
	v_max_f32_e32 v240, v4, v4
	v_max_f32_e32 v241, v5, v5
	v_max_f32_e32 v242, v6, v6
	v_max_f32_e32 v243, v7, v7
	v_max_f32_e32 v240, 0, v240
	v_max_f32_e32 v241, 0, v241
	v_max_f32_e32 v242, 0, v242
	v_max_f32_e32 v243, 0, v243
	v_mul_f32_e32 v240, v240, v240
	v_mul_f32_e32 v241, v241, v241
	v_mul_f32_e32 v242, v242, v242
	v_mul_f32_e32 v243, v243, v243
	v_cvt_pk_bf16_f32 v238, v240, v241
	v_cvt_pk_bf16_f32 v239, v242, v243
	global_store_dwordx2 v[144:145], v[238:239], off offset:288
	s_branch .LBB0_1310

; #define LAS __attribute__((address_space(3)))
; __global__ void __launch_bounds__(512, 2) mega_fwd(Params p) {
;     extern __shared__ __attribute__((aligned(16))) unsigned char lds_raw[];
;     LAS unsigned char* lds = (LAS unsigned char*)lds_raw;
;     cg::grid_group grid = cg::this_grid();
	.amdhsa_kernel _Z8mega_fwd6Params
		.amdhsa_group_segment_fixed_size 0
		.amdhsa_private_segment_fixed_size 0
		.amdhsa_kernarg_size 592
		.amdhsa_user_sgpr_count 2
		.amdhsa_user_sgpr_dispatch_ptr 0
		.amdhsa_user_sgpr_queue_ptr 0
		.amdhsa_user_sgpr_kernarg_segment_ptr 1
		.amdhsa_user_sgpr_dispatch_id 0
		.amdhsa_user_sgpr_kernarg_preload_length 0
		.amdhsa_user_sgpr_kernarg_preload_offset 0
		.amdhsa_user_sgpr_private_segment_size 0
		.amdhsa_uses_dynamic_stack 0
		.amdhsa_enable_private_segment 0
		.amdhsa_system_sgpr_workgroup_id_x 1
		.amdhsa_system_sgpr_workgroup_id_y 0
		.amdhsa_system_sgpr_workgroup_id_z 0
		.amdhsa_system_sgpr_workgroup_info 0
		.amdhsa_system_vgpr_workitem_id 2
		.amdhsa_next_free_vgpr 244
		.amdhsa_next_free_sgpr 100
		.amdhsa_accum_offset 244
		.amdhsa_reserve_vcc 1
		.amdhsa_float_round_mode_32 0
		.amdhsa_float_round_mode_16_64 0
		.amdhsa_float_denorm_mode_32 3
		.amdhsa_float_denorm_mode_16_64 3
		.amdhsa_dx10_clamp 1
		.amdhsa_ieee_mode 1
		.amdhsa_fp16_overflow 0
		.amdhsa_tg_split 0
		.amdhsa_exception_fp_ieee_invalid_op 0
		.amdhsa_exception_fp_denorm_src 0
		.amdhsa_exception_fp_ieee_div_zero 0
		.amdhsa_exception_fp_ieee_overflow 0
		.amdhsa_exception_fp_ieee_underflow 0
		.amdhsa_exception_fp_ieee_inexact 0
		.amdhsa_exception_int_div_zero 0
	.end_amdhsa_kernel

; #define LAS __attribute__((address_space(3)))
; __global__ void __launch_bounds__(512, 2) mega_fwd(Params p) {
;     extern __shared__ __attribute__((aligned(16))) unsigned char lds_raw[];
;     LAS unsigned char* lds = (LAS unsigned char*)lds_raw;
;     cg::grid_group grid = cg::this_grid();
amdhsa.kernels:
  - .agpr_count:     0
    .args:
      - .offset:         0
        .size:           336
        .value_kind:     by_value
      - .offset:         336
        .size:           4
        .value_kind:     hidden_block_count_x
      - .offset:         340
        .size:           4
        .value_kind:     hidden_block_count_y
      - .offset:         344
        .size:           4
        .value_kind:     hidden_block_count_z
      - .offset:         348
        .size:           2
        .value_kind:     hidden_group_size_x
      - .offset:         350
        .size:           2
        .value_kind:     hidden_group_size_y
      - .offset:         352
        .size:           2
        .value_kind:     hidden_group_size_z
      - .offset:         354
        .size:           2
        .value_kind:     hidden_remainder_x
      - .offset:         356
        .size:           2
        .value_kind:     hidden_remainder_y
      - .offset:         358
        .size:           2
        .value_kind:     hidden_remainder_z
      - .offset:         376
        .size:           8
        .value_kind:     hidden_global_offset_x
      - .offset:         384
        .size:           8
        .value_kind:     hidden_global_offset_y
      - .offset:         392
        .size:           8
        .value_kind:     hidden_global_offset_z
      - .offset:         400
        .size:           2
        .value_kind:     hidden_grid_dims
      - .offset:         424
        .size:           8
        .value_kind:     hidden_multigrid_sync_arg
      - .offset:         456
        .size:           4
        .value_kind:     hidden_dynamic_lds_size
    .group_segment_fixed_size: 0
    .kernarg_segment_align: 8
    .kernarg_segment_size: 592
    .language:       OpenCL C
    .language_version:
      - 2
      - 0
    .max_flat_workgroup_size: 512
    .name:           _Z8mega_fwd6Params
    .private_segment_fixed_size: 0
    .sgpr_count:     106
    .sgpr_spill_count: 130
    .symbol:         _Z8mega_fwd6Params.kd
    .uniform_work_group_size: 1
    .uses_dynamic_stack: false
    .vgpr_count:     244
    .vgpr_spill_count: 0
    .wavefront_size: 64
